# attention: bias/block-mean LDS tables copied only by a workgroup's first unit (same b,h for its 4 units when G==256; later copy loops run zero trips); on top of v65
# baseline (speedup 1.0000x reference)
; __device__ __forceinline__ void attn_phase(LAS unsigned char* lds, const bf16_t* QKV, const float* kmean, const float* biasT, bf16_t* O, int G, int wg) {
;     ...
;         ATT_LOAD(0);
;         int tl = tid; asm volatile("" : "+v"(tl));
;         for (int i = tl; i < 2048; i += NTHREADS) BT[i] = biasT[h * 2048 + i];
.LBB0_1313:
	s_lshl_b32 s0, s53, 8
	s_and_b32 s46, s0, 0x7800
	s_lshl_b32 s55, s54, 8
	s_or_b32 s0, s55, s46
	s_mov_b32 s1, s17
	v_lshl_add_u64 v[0:1], s[0:1], 0, v[146:147]
	v_mov_b64_e32 v[2:3], s[14:15]
	s_and_b32 s47, s53, 7
	v_mad_u64_u32 v[4:5], s[38:39], v0, s89, v[2:3]
	v_mad_i32_i24 v5, v1, s89, v5
	s_lshl_b32 s16, s47, 8
	v_lshl_add_u64 v[0:1], v[4:5], 0, s[16:17]
	v_or_b32_e32 v4, s0, v144
	v_mad_u64_u32 v[2:3], s[38:39], v4, s89, v[2:3]
	v_lshl_add_u64 v[2:3], v[2:3], 0, s[16:17]
	v_lshl_add_u64 v[0:1], v[0:1], 0, v[174:175]
	v_lshl_add_u64 v[2:3], v[148:149], 1, v[2:3]
	s_barrier
	global_load_dwordx4 v[40:43], v[0:1], off offset:2064
	global_load_dwordx4 v[44:47], v[0:1], off offset:2048
	v_add_co_u32_e32 v0, vcc, 0x1000, v2
	v_lshl_add_u64 v[4:5], v[2:3], 0, s[94:95]
	s_nop 0
	v_addc_co_u32_e32 v1, vcc, 0, v3, vcc
	global_load_dwordx4 v[32:35], v[0:1], off
	global_load_dwordx4 v[36:39], v[4:5], off offset:16
	v_mov_b32_e32 v0, v169
	s_movk_i32 s1, 0x800
	s_lshr_b32 s16, s53, 8
	s_cmp_lg_u32 s16, 0
	s_cselect_b32 s16, 0, s1
	s_cmp_eq_u32 s28, 0x100
	s_cselect_b32 s1, s16, s1
	s_nop 0
	v_cmp_gt_i32_e32 vcc, s1, v0
	s_and_saveexec_b64 s[38:39], vcc
	s_cbranch_execz .LBB0_1321
	v_max_i32_e32 v1, 0x600, v0
	v_sub_u32_e32 v1, v1, v0
	v_add_u32_e32 v1, 0x1ff, v1
	s_movk_i32 s1, 0x1ff
	v_cmp_lt_u32_e32 vcc, s1, v1
	s_mov_b64 s[48:49], -1
	v_mov_b32_e32 v2, v0
	s_and_saveexec_b64 s[44:45], vcc
	s_cbranch_execz .LBB0_1318
	v_lshrrev_b32_e32 v1, 9, v1
	v_add_u32_e32 v4, 1, v1
	s_lshl_b32 s1, s47, 11
	v_and_b32_e32 v5, 0xfffffe, v4
	v_add_u32_e32 v1, 0x200, v0
	s_add_i32 s48, 0, 0x1a000
	s_mov_b32 s16, s1
	v_lshl_add_u32 v6, v0, 2, s48
	s_mov_b64 s[48:49], 0
	v_mov_b32_e32 v7, v5
	v_mov_b64_e32 v[2:3], v[0:1]

; #define LAS __attribute__((address_space(3)))
; __device__ __forceinline__ void attn_phase(LAS unsigned char* lds, const bf16_t* QKV, const float* kmean, const float* biasT, bf16_t* O, int G, int wg) {
;     ...
;         LAS float* KM = (LAS float*)(lds + BT_OFF + 8192);
;         if (ob > 3) { for (int i = tl; i < ob * 128; i += NTHREADS) KM[i] = kmean[(size_t)(bh * 8) * 128 + i]; }
.LBB0_1321:
	s_or_b64 exec, exec, s[38:39]
	s_cmp_lt_u32 s54, 4
	s_cbranch_scc1 .LBB0_1331
	s_lshl_b32 s1, s54, 7
	s_lshr_b32 s16, s53, 8
	s_cmp_lg_u32 s16, 0
	s_cselect_b32 s16, 0, s1
	s_cmp_eq_u32 s28, 0x100
	s_cselect_b32 s1, s16, s1
	v_cmp_gt_i32_e32 vcc, s1, v0
	s_and_saveexec_b64 s[38:39], vcc
	s_cbranch_execz .LBB0_1330
	v_add_u32_e32 v1, 0x200, v0
	v_max_i32_e32 v2, s1, v1
	v_xad_u32 v2, v0, -1, v2
	s_movk_i32 s16, 0x1ff
	v_cmp_lt_u32_e32 vcc, s16, v2
	s_mov_b64 s[48:49], -1
	s_and_saveexec_b64 s[44:45], vcc
	s_cbranch_execz .LBB0_1327
	s_and_b32 s16, s53, 0x7f
	s_lshl_b32 s16, s16, 12
	v_readlane_b32 s48, v252, 44
	v_lshrrev_b32_e32 v2, 9, v2
	v_readlane_b32 s49, v252, 45
	s_add_u32 s48, s48, s16
	v_add_u32_e32 v4, 1, v2
	s_addc_u32 s49, s49, 0
	v_and_b32_e32 v5, 0xfffffe, v4
	s_add_i32 s16, 0, 0x1c000
	v_lshl_add_u32 v6, v0, 2, s16
	s_mov_b64 s[50:51], 0
	v_mov_b32_e32 v7, v5
	v_mov_b64_e32 v[2:3], v[0:1]
